# plus Q-up rope epilogue: 32 serialized cos/sin loads hoisted into two batched groups
# speedup vs baseline: 1.0268x; 1.0072x over previous
; DEV u16 f2bf(float f) { return (u16)(pk2bf(f, 0.f) & 0xffffu); }
; DEV void phase_p2(const Params& p, int l, unsigned char* smem) {
;     ...
; #pragma unroll
;     for (int mi = 0; mi < 2; ++mi)
; #pragma unroll
;       for (int r = 0; r < 16; ++r) {
;         const int row = (w >> 1) * 64 + mi * 32 + (r & 3) + 8 * (r >> 2) + 4 * (lane >> 5);
;         const int m = mt * 128 + row;
;         const float rs = rsqrtf(ss[row] * (1.0f / 768.0f) + EPS) * QSCALE;
;         float v0 = acc[mi][0][r] * rs, v1 = acc[mi][1][r] * rs;
;         if (rope) {
;           const int pos = pos_of(m);
;           const float c = ROPE[(pos * 32 + (lane & 31)) * 2], s = ROPE[(pos * 32 + (lane & 31)) * 2 + 1];
;           const float a = v0 * c - v1 * s, b = v0 * s + v1 * c;
;           v0 = a; v1 = b;
;         }
;         const int col = (w & 1) * 64 + (lane & 31);
;         sC[row * LDC + col] = f2bf(v0);
;         sC[row * LDC + col + 32] = f2bf(v1);
.LBB0_639:
	s_lshl_b32 s39, s36, 7
	s_and_saveexec_b64 s[12:13], s[4:5]
	s_cbranch_execz .Lqrope_b1
	v_add_u32_e32 v220, s39, v124
	v_and_b32_e32 v221, 0xfc4, v220
	v_cmp_gt_i32_e32 vcc, s35, v220
	s_nop 1
	v_cndmask_b32_e32 v220, v126, v221, vcc
	v_lshl_or_b32 v220, v220, 8, v180
	global_load_dwordx2 v[188:189], v220, s[62:63]
	v_add_u32_e32 v220, s39, v128
	v_and_b32_e32 v221, 0xfc5, v220
	v_cmp_gt_i32_e32 vcc, s35, v220
	s_nop 1
	v_cndmask_b32_e32 v220, v129, v221, vcc
	v_lshl_or_b32 v220, v220, 8, v180
	global_load_dwordx2 v[190:191], v220, s[62:63]
	v_add_u32_e32 v220, s39, v130
	v_and_b32_e32 v221, 0xfc6, v220
	v_cmp_gt_i32_e32 vcc, s35, v220
	s_nop 1
	v_cndmask_b32_e32 v220, v131, v221, vcc
	v_lshl_or_b32 v220, v220, 8, v180
	global_load_dwordx2 v[192:193], v220, s[62:63]
	v_add_u32_e32 v220, s39, v132
	v_and_b32_e32 v221, 0xfc7, v220
	v_cmp_gt_i32_e32 vcc, s35, v220
	s_nop 1
	v_cndmask_b32_e32 v220, v133, v221, vcc
	v_lshl_or_b32 v220, v220, 8, v180
	global_load_dwordx2 v[194:195], v220, s[62:63]
	v_add_u32_e32 v220, s39, v134
	v_and_b32_e32 v221, 0xfcc, v220
	v_cmp_gt_i32_e32 vcc, s35, v220
	s_nop 1
	v_cndmask_b32_e32 v220, v135, v221, vcc
	v_lshl_or_b32 v220, v220, 8, v180
	global_load_dwordx2 v[196:197], v220, s[62:63]
	v_add_u32_e32 v220, s39, v136
	v_and_b32_e32 v221, 0xfcd, v220
	v_cmp_gt_i32_e32 vcc, s35, v220
	s_nop 1
	v_cndmask_b32_e32 v220, v137, v221, vcc
	v_lshl_or_b32 v220, v220, 8, v180
	global_load_dwordx2 v[198:199], v220, s[62:63]
	v_add_u32_e32 v220, s39, v138
	v_and_b32_e32 v221, 0xfce, v220
	v_cmp_gt_i32_e32 vcc, s35, v220
	s_nop 1
	v_cndmask_b32_e32 v220, v139, v221, vcc
	v_lshl_or_b32 v220, v220, 8, v180
	global_load_dwordx2 v[200:201], v220, s[62:63]
	v_add_u32_e32 v220, s39, v140
	v_and_b32_e32 v221, 0xfcf, v220
	v_cmp_gt_i32_e32 vcc, s35, v220
	s_nop 1
	v_cndmask_b32_e32 v220, v141, v221, vcc
	v_lshl_or_b32 v220, v220, 8, v180
	global_load_dwordx2 v[202:203], v220, s[62:63]
	v_add_u32_e32 v220, s39, v142
	v_and_b32_e32 v221, 0xfd4, v220
	v_cmp_gt_i32_e32 vcc, s35, v220
	s_nop 1
	v_cndmask_b32_e32 v220, v126, v221, vcc
	v_lshl_or_b32 v220, v220, 8, v180
	global_load_dwordx2 v[204:205], v220, s[62:63]
	v_add_u32_e32 v220, s39, v143
	v_and_b32_e32 v221, 0xfd5, v220
	v_cmp_gt_i32_e32 vcc, s35, v220
	s_nop 1
	v_cndmask_b32_e32 v220, v129, v221, vcc
	v_lshl_or_b32 v220, v220, 8, v180
	global_load_dwordx2 v[206:207], v220, s[62:63]
	v_add_u32_e32 v220, s39, v144
	v_and_b32_e32 v221, 0xfd6, v220
	v_cmp_gt_i32_e32 vcc, s35, v220
	s_nop 1
	v_cndmask_b32_e32 v220, v131, v221, vcc
	v_lshl_or_b32 v220, v220, 8, v180
	global_load_dwordx2 v[208:209], v220, s[62:63]
	v_add_u32_e32 v220, s39, v145
	v_and_b32_e32 v221, 0xfd7, v220
	v_cmp_gt_i32_e32 vcc, s35, v220
	s_nop 1
	v_cndmask_b32_e32 v220, v133, v221, vcc
	v_lshl_or_b32 v220, v220, 8, v180
	global_load_dwordx2 v[210:211], v220, s[62:63]
	v_add_u32_e32 v220, s39, v146
	v_and_b32_e32 v221, 0xfdc, v220
	v_cmp_gt_i32_e32 vcc, s35, v220
	s_nop 1
	v_cndmask_b32_e32 v220, v135, v221, vcc
	v_lshl_or_b32 v220, v220, 8, v180
	global_load_dwordx2 v[212:213], v220, s[62:63]
	v_add_u32_e32 v220, s39, v147
	v_and_b32_e32 v221, 0xfdd, v220
	v_cmp_gt_i32_e32 vcc, s35, v220
	s_nop 1
	v_cndmask_b32_e32 v220, v137, v221, vcc
	v_lshl_or_b32 v220, v220, 8, v180
	global_load_dwordx2 v[214:215], v220, s[62:63]
	v_add_u32_e32 v220, s39, v148
	v_and_b32_e32 v221, 0xfde, v220
	v_cmp_gt_i32_e32 vcc, s35, v220
	s_nop 1
	v_cndmask_b32_e32 v220, v139, v221, vcc
	v_lshl_or_b32 v220, v220, 8, v180
	global_load_dwordx2 v[216:217], v220, s[62:63]
	v_add_u32_e32 v220, s39, v149
	v_and_b32_e32 v221, 0xfdf, v220
	v_cmp_gt_i32_e32 vcc, s35, v220
	s_nop 1
	v_cndmask_b32_e32 v220, v141, v221, vcc
	v_lshl_or_b32 v220, v220, 8, v180
	global_load_dwordx2 v[218:219], v220, s[62:63]
.Lqrope_b1:
	s_or_b64 exec, exec, s[12:13]
	ds_read_b32 v64, v125 offset:36864
	s_lshl_b32 s39, s36, 7
	s_waitcnt lgkmcnt(0)
	v_fmamk_f32 v64, v64, 0x3aaaaaab, v233
	v_mul_f32_e32 v65, 0x4b800000, v64
	v_cmp_gt_f32_e32 vcc, s86, v64
	s_nop 1
	v_cndmask_b32_e32 v64, v64, v65, vcc
	v_rsq_f32_e32 v65, v64
	v_mov_b32_e32 v64, v32
	v_mul_f32_e32 v32, 0x45800000, v65
	v_cndmask_b32_e32 v32, v65, v32, vcc
	v_mul_f32_e32 v32, 0x3dd53b94, v32
	v_mov_b32_e32 v65, v48
	v_pk_mul_f32 v[64:65], v[64:65], v[32:33] op_sel_hi:[1,0]
	s_and_saveexec_b64 s[12:13], s[4:5]
	s_cbranch_execz .LBB0_641
	s_waitcnt vmcnt(15)
	v_pk_mul_f32 v[70:71], v[64:65], v[188:189] op_sel_hi:[0,1]
	v_pk_mul_f32 v[68:69], v[64:65], v[188:189] op_sel:[1,1] op_sel_hi:[1,0]
	v_pk_fma_f32 v[64:65], v[64:65], v[188:189], v[70:71] op_sel:[1,1,0] op_sel_hi:[1,0,1] neg_lo:[0,0,1] neg_hi:[0,0,1]
	s_nop 0
	v_add_f32_e32 v64, v68, v70
.LBB0_641:
	s_or_b64 exec, exec, s[12:13]
	v_cvt_pk_bf16_f32 v32, v65, s0
	v_add_u32_e32 v48, v123, v127
	ds_write_b16 v48, v32
	v_cvt_pk_bf16_f32 v32, v64, s0
	ds_write_b16 v48, v32 offset:64
	ds_read_b32 v32, v125 offset:36868
	s_waitcnt lgkmcnt(0)
	v_fmamk_f32 v32, v32, 0x3aaaaaab, v233
	v_cmp_gt_f32_e32 vcc, s86, v32
	v_mul_f32_e32 v48, 0x4b800000, v32
	s_nop 0
	v_cndmask_b32_e32 v32, v32, v48, vcc
	v_rsq_f32_e32 v32, v32
	s_nop 0
	v_mul_f32_e32 v48, 0x45800000, v32
	v_cndmask_b32_e32 v32, v32, v48, vcc
	v_mul_f32_e32 v32, 0x3dd53b94, v32
	v_mov_b32_e32 v48, v33
	v_pk_mul_f32 v[32:33], v[48:49], v[32:33] op_sel_hi:[1,0]
	s_and_saveexec_b64 s[12:13], s[4:5]
	s_cbranch_execz .LBB0_643
	s_waitcnt vmcnt(14)
	v_pk_mul_f32 v[66:67], v[32:33], v[190:191] op_sel_hi:[0,1]
	v_pk_mul_f32 v[64:65], v[32:33], v[190:191] op_sel:[1,1] op_sel_hi:[1,0]
	v_pk_fma_f32 v[32:33], v[32:33], v[190:191], v[66:67] op_sel:[1,1,0] op_sel_hi:[1,0,1] neg_lo:[0,0,1] neg_hi:[0,0,1]
	s_nop 0
	v_add_f32_e32 v32, v64, v66
; DEV u16 f2bf(float f) { return (u16)(pk2bf(f, 0.f) & 0xffffu); }
; DEV void phase_p2(const Params& p, int l, unsigned char* smem) {
;     ...
;     for (int mi = 0; mi < 2; ++mi)
; #pragma unroll
;       for (int r = 0; r < 16; ++r) {
;         const int row = (w >> 1) * 64 + mi * 32 + (r & 3) + 8 * (r >> 2) + 4 * (lane >> 5);
;         const int m = mt * 128 + row;
;         const float rs = rsqrtf(ss[row] * (1.0f / 768.0f) + EPS) * QSCALE;
;         float v0 = acc[mi][0][r] * rs, v1 = acc[mi][1][r] * rs;
;         if (rope) {
;           const int pos = pos_of(m);
;           const float c = ROPE[(pos * 32 + (lane & 31)) * 2], s = ROPE[(pos * 32 + (lane & 31)) * 2 + 1];
;           const float a = v0 * c - v1 * s, b = v0 * s + v1 * c;
;           v0 = a; v1 = b;
;         }
;         const int col = (w & 1) * 64 + (lane & 31);
;         sC[row * LDC + col] = f2bf(v0);
;         sC[row * LDC + col + 32] = f2bf(v1);
.LBB0_643:
	s_or_b64 exec, exec, s[12:13]
	v_cvt_pk_bf16_f32 v32, v32, s0
	ds_write_b16 v166, v32 offset:64
	ds_read_b32 v32, v125 offset:36872
	v_cvt_pk_bf16_f32 v33, v33, s0
	ds_write_b16 v166, v33
	v_mov_b32_e32 v48, v34
	v_mov_b32_e32 v49, v50
	s_waitcnt lgkmcnt(1)
	v_fmamk_f32 v32, v32, 0x3aaaaaab, v233
	v_cmp_gt_f32_e32 vcc, s86, v32
	v_mul_f32_e32 v33, 0x4b800000, v32
	s_nop 0
	v_cndmask_b32_e32 v32, v32, v33, vcc
	v_rsq_f32_e32 v32, v32
	s_nop 0
	v_mul_f32_e32 v33, 0x45800000, v32
	v_cndmask_b32_e32 v32, v32, v33, vcc
	v_mul_f32_e32 v32, 0x3dd53b94, v32
	v_pk_mul_f32 v[32:33], v[48:49], v[32:33] op_sel_hi:[1,0]
	s_and_saveexec_b64 s[12:13], s[4:5]
	s_cbranch_execz .LBB0_645
	s_waitcnt vmcnt(13)
	v_pk_mul_f32 v[66:67], v[32:33], v[192:193] op_sel_hi:[0,1]
	v_pk_mul_f32 v[64:65], v[32:33], v[192:193] op_sel:[1,1] op_sel_hi:[1,0]
	v_pk_fma_f32 v[32:33], v[32:33], v[192:193], v[66:67] op_sel:[1,1,0] op_sel_hi:[1,0,1] neg_lo:[0,0,1] neg_hi:[0,0,1]
	s_nop 0
	v_add_f32_e32 v32, v64, v66
.LBB0_645:
	s_or_b64 exec, exec, s[12:13]
	v_cvt_pk_bf16_f32 v32, v32, s0
	ds_write_b16 v167, v32 offset:64
	ds_read_b32 v32, v125 offset:36876
	v_cvt_pk_bf16_f32 v33, v33, s0
	ds_write_b16 v167, v33
	v_mov_b32_e32 v50, v35
	s_waitcnt lgkmcnt(1)
	v_fmamk_f32 v32, v32, 0x3aaaaaab, v233
	v_cmp_gt_f32_e32 vcc, s86, v32
	v_mul_f32_e32 v33, 0x4b800000, v32
	s_nop 0
	v_cndmask_b32_e32 v32, v32, v33, vcc
	v_rsq_f32_e32 v32, v32
	s_nop 0
	v_mul_f32_e32 v33, 0x45800000, v32
	v_cndmask_b32_e32 v32, v32, v33, vcc
	v_mul_f32_e32 v32, 0x3dd53b94, v32
	v_pk_mul_f32 v[32:33], v[50:51], v[32:33] op_sel_hi:[1,0]
	s_and_saveexec_b64 s[12:13], s[4:5]
	s_cbranch_execz .LBB0_647
	s_waitcnt vmcnt(12)
	v_pk_mul_f32 v[50:51], v[32:33], v[194:195] op_sel_hi:[0,1]
	v_pk_mul_f32 v[48:49], v[32:33], v[194:195] op_sel:[1,1] op_sel_hi:[1,0]
	v_pk_fma_f32 v[32:33], v[32:33], v[194:195], v[50:51] op_sel:[1,1,0] op_sel_hi:[1,0,1] neg_lo:[0,0,1] neg_hi:[0,0,1]
	s_nop 0
	v_add_f32_e32 v32, v48, v50
.LBB0_647:
	s_or_b64 exec, exec, s[12:13]
	v_cvt_pk_bf16_f32 v32, v32, s0
	ds_write_b16 v168, v32 offset:64
	ds_read_b32 v32, v125 offset:36896
	v_cvt_pk_bf16_f32 v33, v33, s0
	ds_write_b16 v168, v33
	v_mov_b32_e32 v34, v36
	v_mov_b32_e32 v35, v52
	s_waitcnt lgkmcnt(1)
	v_fmamk_f32 v32, v32, 0x3aaaaaab, v233
	v_cmp_gt_f32_e32 vcc, s86, v32
	v_mul_f32_e32 v33, 0x4b800000, v32
	s_nop 0
	v_cndmask_b32_e32 v32, v32, v33, vcc
	v_rsq_f32_e32 v32, v32
	s_nop 0
	v_mul_f32_e32 v33, 0x45800000, v32
	v_cndmask_b32_e32 v32, v32, v33, vcc
	v_mul_f32_e32 v32, 0x3dd53b94, v32
	v_pk_mul_f32 v[32:33], v[34:35], v[32:33] op_sel_hi:[1,0]
	s_and_saveexec_b64 s[12:13], s[4:5]
	s_cbranch_execz .LBB0_649
	s_waitcnt vmcnt(11)
	v_pk_mul_f32 v[50:51], v[32:33], v[196:197] op_sel_hi:[0,1]
	v_pk_mul_f32 v[48:49], v[32:33], v[196:197] op_sel:[1,1] op_sel_hi:[1,0]
	v_pk_fma_f32 v[32:33], v[32:33], v[196:197], v[50:51] op_sel:[1,1,0] op_sel_hi:[1,0,1] neg_lo:[0,0,1] neg_hi:[0,0,1]
	s_nop 0
	v_add_f32_e32 v32, v48, v50
.LBB0_649:
	s_or_b64 exec, exec, s[12:13]
	v_cvt_pk_bf16_f32 v32, v32, s0
	ds_write_b16 v169, v32 offset:64
	ds_read_b32 v32, v125 offset:36900
	v_cvt_pk_bf16_f32 v33, v33, s0
	ds_write_b16 v169, v33
	v_mov_b32_e32 v52, v37
	s_waitcnt lgkmcnt(1)
	v_fmamk_f32 v32, v32, 0x3aaaaaab, v233
	v_cmp_gt_f32_e32 vcc, s86, v32
	v_mul_f32_e32 v33, 0x4b800000, v32
	s_nop 0
	v_cndmask_b32_e32 v32, v32, v33, vcc
	v_rsq_f32_e32 v32, v32
	s_nop 0
	v_mul_f32_e32 v33, 0x45800000, v32
	v_cndmask_b32_e32 v32, v32, v33, vcc
	v_mul_f32_e32 v32, 0x3dd53b94, v32
	v_pk_mul_f32 v[32:33], v[52:53], v[32:33] op_sel_hi:[1,0]
	s_and_saveexec_b64 s[12:13], s[4:5]
	s_cbranch_execz .LBB0_651
	s_waitcnt vmcnt(10)
	v_pk_mul_f32 v[48:49], v[32:33], v[198:199] op_sel_hi:[0,1]
	v_pk_mul_f32 v[36:37], v[32:33], v[198:199] op_sel:[1,1] op_sel_hi:[1,0]
	v_pk_fma_f32 v[32:33], v[32:33], v[198:199], v[48:49] op_sel:[1,1,0] op_sel_hi:[1,0,1] neg_lo:[0,0,1] neg_hi:[0,0,1]
	s_nop 0
	v_add_f32_e32 v32, v36, v48
.LBB0_651:
	s_or_b64 exec, exec, s[12:13]
	v_cvt_pk_bf16_f32 v32, v32, s0
	ds_write_b16 v170, v32 offset:64
	ds_read_b32 v32, v125 offset:36904
	v_cvt_pk_bf16_f32 v33, v33, s0
	ds_write_b16 v170, v33
	v_mov_b32_e32 v34, v38
	v_mov_b32_e32 v35, v54
	s_waitcnt lgkmcnt(1)
	v_fmamk_f32 v32, v32, 0x3aaaaaab, v233
	v_cmp_gt_f32_e32 vcc, s86, v32
	v_mul_f32_e32 v33, 0x4b800000, v32
	s_nop 0
	v_cndmask_b32_e32 v32, v32, v33, vcc
	v_rsq_f32_e32 v32, v32
	s_nop 0
	v_mul_f32_e32 v33, 0x45800000, v32
	v_cndmask_b32_e32 v32, v32, v33, vcc
	v_mul_f32_e32 v32, 0x3dd53b94, v32
	v_pk_mul_f32 v[32:33], v[34:35], v[32:33] op_sel_hi:[1,0]
	s_and_saveexec_b64 s[12:13], s[4:5]
	s_cbranch_execz .LBB0_653
	s_waitcnt vmcnt(9)
	v_pk_mul_f32 v[48:49], v[32:33], v[200:201] op_sel_hi:[0,1]
	v_pk_mul_f32 v[36:37], v[32:33], v[200:201] op_sel:[1,1] op_sel_hi:[1,0]
	v_pk_fma_f32 v[32:33], v[32:33], v[200:201], v[48:49] op_sel:[1,1,0] op_sel_hi:[1,0,1] neg_lo:[0,0,1] neg_hi:[0,0,1]
	s_nop 0
	v_add_f32_e32 v32, v36, v48
.LBB0_653:
	s_or_b64 exec, exec, s[12:13]
	v_cvt_pk_bf16_f32 v32, v32, s0
	ds_write_b16 v171, v32 offset:64
	ds_read_b32 v32, v125 offset:36908
	v_cvt_pk_bf16_f32 v33, v33, s0
	ds_write_b16 v171, v33
	v_mov_b32_e32 v54, v39
	s_waitcnt lgkmcnt(1)
	v_fmamk_f32 v32, v32, 0x3aaaaaab, v233
	v_cmp_gt_f32_e32 vcc, s86, v32
	v_mul_f32_e32 v33, 0x4b800000, v32
	s_nop 0
	v_cndmask_b32_e32 v32, v32, v33, vcc
	v_rsq_f32_e32 v32, v32
	s_nop 0
	v_mul_f32_e32 v33, 0x45800000, v32
	v_cndmask_b32_e32 v32, v32, v33, vcc
	v_mul_f32_e32 v32, 0x3dd53b94, v32
	v_pk_mul_f32 v[32:33], v[54:55], v[32:33] op_sel_hi:[1,0]
	s_and_saveexec_b64 s[12:13], s[4:5]
	s_cbranch_execz .LBB0_655
	s_waitcnt vmcnt(8)
	v_pk_mul_f32 v[38:39], v[32:33], v[202:203] op_sel_hi:[0,1]
	v_pk_mul_f32 v[36:37], v[32:33], v[202:203] op_sel:[1,1] op_sel_hi:[1,0]
	v_pk_fma_f32 v[32:33], v[32:33], v[202:203], v[38:39] op_sel:[1,1,0] op_sel_hi:[1,0,1] neg_lo:[0,0,1] neg_hi:[0,0,1]
	s_nop 0
	v_add_f32_e32 v32, v36, v38
; DEV u16 f2bf(float f) { return (u16)(pk2bf(f, 0.f) & 0xffffu); }
; DEV void phase_p2(const Params& p, int l, unsigned char* smem) {
;     ...
;     for (int mi = 0; mi < 2; ++mi)
; #pragma unroll
;       for (int r = 0; r < 16; ++r) {
;         const int row = (w >> 1) * 64 + mi * 32 + (r & 3) + 8 * (r >> 2) + 4 * (lane >> 5);
;         const int m = mt * 128 + row;
;         const float rs = rsqrtf(ss[row] * (1.0f / 768.0f) + EPS) * QSCALE;
;         float v0 = acc[mi][0][r] * rs, v1 = acc[mi][1][r] * rs;
;         if (rope) {
;           const int pos = pos_of(m);
;           const float c = ROPE[(pos * 32 + (lane & 31)) * 2], s = ROPE[(pos * 32 + (lane & 31)) * 2 + 1];
;           const float a = v0 * c - v1 * s, b = v0 * s + v1 * c;
;           v0 = a; v1 = b;
;         }
;         const int col = (w & 1) * 64 + (lane & 31);
;         sC[row * LDC + col] = f2bf(v0);
;         sC[row * LDC + col + 32] = f2bf(v1);
.LBB0_655:
	s_or_b64 exec, exec, s[12:13]
	v_cvt_pk_bf16_f32 v32, v32, s0
	ds_write_b16 v172, v32 offset:64
	ds_read_b32 v32, v125 offset:36928
	v_cvt_pk_bf16_f32 v33, v33, s0
	ds_write_b16 v172, v33
	v_mov_b32_e32 v34, v40
	v_mov_b32_e32 v35, v56
	s_waitcnt lgkmcnt(1)
	v_fmamk_f32 v32, v32, 0x3aaaaaab, v233
	v_cmp_gt_f32_e32 vcc, s86, v32
	v_mul_f32_e32 v33, 0x4b800000, v32
	s_nop 0
	v_cndmask_b32_e32 v32, v32, v33, vcc
	v_rsq_f32_e32 v32, v32
	s_nop 0
	v_mul_f32_e32 v33, 0x45800000, v32
	v_cndmask_b32_e32 v32, v32, v33, vcc
	v_mul_f32_e32 v32, 0x3dd53b94, v32
	v_pk_mul_f32 v[32:33], v[34:35], v[32:33] op_sel_hi:[1,0]
	s_and_saveexec_b64 s[12:13], s[4:5]
	s_cbranch_execz .LBB0_657
	s_waitcnt vmcnt(7)
	v_pk_mul_f32 v[38:39], v[32:33], v[204:205] op_sel_hi:[0,1]
	v_pk_mul_f32 v[36:37], v[32:33], v[204:205] op_sel:[1,1] op_sel_hi:[1,0]
	v_pk_fma_f32 v[32:33], v[32:33], v[204:205], v[38:39] op_sel:[1,1,0] op_sel_hi:[1,0,1] neg_lo:[0,0,1] neg_hi:[0,0,1]
	s_nop 0
	v_add_f32_e32 v32, v36, v38
.LBB0_657:
	s_or_b64 exec, exec, s[12:13]
	v_cvt_pk_bf16_f32 v32, v32, s0
	ds_write_b16 v173, v32 offset:64
	ds_read_b32 v32, v125 offset:36932
	v_cvt_pk_bf16_f32 v33, v33, s0
	ds_write_b16 v173, v33
	v_mov_b32_e32 v56, v41
	s_waitcnt lgkmcnt(1)
	v_fmamk_f32 v32, v32, 0x3aaaaaab, v233
	v_cmp_gt_f32_e32 vcc, s86, v32
	v_mul_f32_e32 v33, 0x4b800000, v32
	s_nop 0
	v_cndmask_b32_e32 v32, v32, v33, vcc
	v_rsq_f32_e32 v32, v32
	s_nop 0
	v_mul_f32_e32 v33, 0x45800000, v32
	v_cndmask_b32_e32 v32, v32, v33, vcc
	v_mul_f32_e32 v32, 0x3dd53b94, v32
	v_pk_mul_f32 v[32:33], v[56:57], v[32:33] op_sel_hi:[1,0]
	s_and_saveexec_b64 s[12:13], s[4:5]
	s_cbranch_execz .LBB0_659
	s_waitcnt vmcnt(6)
	v_pk_mul_f32 v[38:39], v[32:33], v[206:207] op_sel_hi:[0,1]
	v_pk_mul_f32 v[36:37], v[32:33], v[206:207] op_sel:[1,1] op_sel_hi:[1,0]
	v_pk_fma_f32 v[32:33], v[32:33], v[206:207], v[38:39] op_sel:[1,1,0] op_sel_hi:[1,0,1] neg_lo:[0,0,1] neg_hi:[0,0,1]
	s_nop 0
	v_add_f32_e32 v32, v36, v38
.LBB0_659:
	s_or_b64 exec, exec, s[12:13]
	v_cvt_pk_bf16_f32 v32, v32, s0
	ds_write_b16 v174, v32 offset:64
	ds_read_b32 v32, v125 offset:36936
	v_cvt_pk_bf16_f32 v33, v33, s0
	ds_write_b16 v174, v33
	v_mov_b32_e32 v34, v42
	v_mov_b32_e32 v35, v58
	s_waitcnt lgkmcnt(1)
	v_fmamk_f32 v32, v32, 0x3aaaaaab, v233
	v_cmp_gt_f32_e32 vcc, s86, v32
	v_mul_f32_e32 v33, 0x4b800000, v32
	s_nop 0
	v_cndmask_b32_e32 v32, v32, v33, vcc
	v_rsq_f32_e32 v32, v32
	s_nop 0
	v_mul_f32_e32 v33, 0x45800000, v32
	v_cndmask_b32_e32 v32, v32, v33, vcc
	v_mul_f32_e32 v32, 0x3dd53b94, v32
	v_pk_mul_f32 v[32:33], v[34:35], v[32:33] op_sel_hi:[1,0]
	s_and_saveexec_b64 s[12:13], s[4:5]
	s_cbranch_execz .LBB0_661
	s_waitcnt vmcnt(5)
	v_pk_mul_f32 v[38:39], v[32:33], v[208:209] op_sel_hi:[0,1]
	v_pk_mul_f32 v[36:37], v[32:33], v[208:209] op_sel:[1,1] op_sel_hi:[1,0]
	v_pk_fma_f32 v[32:33], v[32:33], v[208:209], v[38:39] op_sel:[1,1,0] op_sel_hi:[1,0,1] neg_lo:[0,0,1] neg_hi:[0,0,1]
	s_nop 0
	v_add_f32_e32 v32, v36, v38
.LBB0_661:
	s_or_b64 exec, exec, s[12:13]
	v_cvt_pk_bf16_f32 v32, v32, s0
	ds_write_b16 v175, v32 offset:64
	ds_read_b32 v32, v125 offset:36940
	v_cvt_pk_bf16_f32 v33, v33, s0
	ds_write_b16 v175, v33
	v_mov_b32_e32 v58, v43
	s_waitcnt lgkmcnt(1)
	v_fmamk_f32 v32, v32, 0x3aaaaaab, v233
	v_cmp_gt_f32_e32 vcc, s86, v32
	v_mul_f32_e32 v33, 0x4b800000, v32
	s_nop 0
	v_cndmask_b32_e32 v32, v32, v33, vcc
	v_rsq_f32_e32 v32, v32
	s_nop 0
	v_mul_f32_e32 v33, 0x45800000, v32
	v_cndmask_b32_e32 v32, v32, v33, vcc
	v_mul_f32_e32 v32, 0x3dd53b94, v32
	v_pk_mul_f32 v[32:33], v[58:59], v[32:33] op_sel_hi:[1,0]
	s_and_saveexec_b64 s[12:13], s[4:5]
	s_cbranch_execz .LBB0_663
	s_waitcnt vmcnt(4)
	v_pk_mul_f32 v[38:39], v[32:33], v[210:211] op_sel_hi:[0,1]
	v_pk_mul_f32 v[36:37], v[32:33], v[210:211] op_sel:[1,1] op_sel_hi:[1,0]
	v_pk_fma_f32 v[32:33], v[32:33], v[210:211], v[38:39] op_sel:[1,1,0] op_sel_hi:[1,0,1] neg_lo:[0,0,1] neg_hi:[0,0,1]
	s_nop 0
	v_add_f32_e32 v32, v36, v38
.LBB0_663:
	s_or_b64 exec, exec, s[12:13]
	v_cvt_pk_bf16_f32 v32, v32, s0
	ds_write_b16 v176, v32 offset:64
	ds_read_b32 v32, v125 offset:36960
	v_cvt_pk_bf16_f32 v33, v33, s0
	ds_write_b16 v176, v33
	v_mov_b32_e32 v34, v44
	v_mov_b32_e32 v35, v60
	s_waitcnt lgkmcnt(1)
	v_fmamk_f32 v32, v32, 0x3aaaaaab, v233
	v_cmp_gt_f32_e32 vcc, s86, v32
	v_mul_f32_e32 v33, 0x4b800000, v32
	s_nop 0
	v_cndmask_b32_e32 v32, v32, v33, vcc
	v_rsq_f32_e32 v32, v32
	s_nop 0
	v_mul_f32_e32 v33, 0x45800000, v32
	v_cndmask_b32_e32 v32, v32, v33, vcc
	v_mul_f32_e32 v32, 0x3dd53b94, v32
	v_pk_mul_f32 v[32:33], v[34:35], v[32:33] op_sel_hi:[1,0]
	s_and_saveexec_b64 s[12:13], s[4:5]
	s_cbranch_execz .LBB0_665
	s_waitcnt vmcnt(3)
	v_pk_mul_f32 v[38:39], v[32:33], v[212:213] op_sel_hi:[0,1]
	v_pk_mul_f32 v[36:37], v[32:33], v[212:213] op_sel:[1,1] op_sel_hi:[1,0]
	v_pk_fma_f32 v[32:33], v[32:33], v[212:213], v[38:39] op_sel:[1,1,0] op_sel_hi:[1,0,1] neg_lo:[0,0,1] neg_hi:[0,0,1]
	s_nop 0
	v_add_f32_e32 v32, v36, v38
.LBB0_665:
	s_or_b64 exec, exec, s[12:13]
	v_cvt_pk_bf16_f32 v32, v32, s0
	ds_write_b16 v177, v32 offset:64
	ds_read_b32 v32, v125 offset:36964
	v_cvt_pk_bf16_f32 v33, v33, s0
	ds_write_b16 v177, v33
	v_mov_b32_e32 v60, v45
	s_waitcnt lgkmcnt(1)
	v_fmamk_f32 v32, v32, 0x3aaaaaab, v233
	v_cmp_gt_f32_e32 vcc, s86, v32
	v_mul_f32_e32 v33, 0x4b800000, v32
	s_nop 0
	v_cndmask_b32_e32 v32, v32, v33, vcc
	v_rsq_f32_e32 v32, v32
	s_nop 0
	v_mul_f32_e32 v33, 0x45800000, v32
	v_cndmask_b32_e32 v32, v32, v33, vcc
	v_mul_f32_e32 v32, 0x3dd53b94, v32
	v_pk_mul_f32 v[32:33], v[60:61], v[32:33] op_sel_hi:[1,0]
	s_and_saveexec_b64 s[12:13], s[4:5]
	s_cbranch_execz .LBB0_667
	s_waitcnt vmcnt(2)
	v_pk_mul_f32 v[38:39], v[32:33], v[214:215] op_sel_hi:[0,1]
	v_pk_mul_f32 v[36:37], v[32:33], v[214:215] op_sel:[1,1] op_sel_hi:[1,0]
	v_pk_fma_f32 v[32:33], v[32:33], v[214:215], v[38:39] op_sel:[1,1,0] op_sel_hi:[1,0,1] neg_lo:[0,0,1] neg_hi:[0,0,1]
	s_nop 0
	v_add_f32_e32 v32, v36, v38
; DEV u16 f2bf(float f) { return (u16)(pk2bf(f, 0.f) & 0xffffu); }
; DEV void phase_p2(const Params& p, int l, unsigned char* smem) {
;     ...
;     for (int mi = 0; mi < 2; ++mi)
; #pragma unroll
;       for (int r = 0; r < 16; ++r) {
;         const int row = (w >> 1) * 64 + mi * 32 + (r & 3) + 8 * (r >> 2) + 4 * (lane >> 5);
;         const int m = mt * 128 + row;
;         const float rs = rsqrtf(ss[row] * (1.0f / 768.0f) + EPS) * QSCALE;
;         float v0 = acc[mi][0][r] * rs, v1 = acc[mi][1][r] * rs;
;         if (rope) {
;           const int pos = pos_of(m);
;           const float c = ROPE[(pos * 32 + (lane & 31)) * 2], s = ROPE[(pos * 32 + (lane & 31)) * 2 + 1];
;           const float a = v0 * c - v1 * s, b = v0 * s + v1 * c;
;           v0 = a; v1 = b;
;         }
;         const int col = (w & 1) * 64 + (lane & 31);
;         sC[row * LDC + col] = f2bf(v0);
;         sC[row * LDC + col + 32] = f2bf(v1);
.LBB0_667:
	s_or_b64 exec, exec, s[12:13]
	v_cvt_pk_bf16_f32 v32, v32, s0
	ds_write_b16 v178, v32 offset:64
	ds_read_b32 v32, v125 offset:36968
	v_cvt_pk_bf16_f32 v33, v33, s0
	ds_write_b16 v178, v33
	v_mov_b32_e32 v34, v46
	v_mov_b32_e32 v35, v62
	s_waitcnt lgkmcnt(1)
	v_fmamk_f32 v32, v32, 0x3aaaaaab, v233
	v_cmp_gt_f32_e32 vcc, s86, v32
	v_mul_f32_e32 v33, 0x4b800000, v32
	s_nop 0
	v_cndmask_b32_e32 v32, v32, v33, vcc
	v_rsq_f32_e32 v32, v32
	s_nop 0
	v_mul_f32_e32 v33, 0x45800000, v32
	v_cndmask_b32_e32 v32, v32, v33, vcc
	v_mul_f32_e32 v32, 0x3dd53b94, v32
	v_pk_mul_f32 v[32:33], v[34:35], v[32:33] op_sel_hi:[1,0]
	s_and_saveexec_b64 s[12:13], s[4:5]
	s_cbranch_execz .LBB0_669
	s_waitcnt vmcnt(1)
	v_pk_mul_f32 v[38:39], v[32:33], v[216:217] op_sel_hi:[0,1]
	v_pk_mul_f32 v[36:37], v[32:33], v[216:217] op_sel:[1,1] op_sel_hi:[1,0]
	v_pk_fma_f32 v[32:33], v[32:33], v[216:217], v[38:39] op_sel:[1,1,0] op_sel_hi:[1,0,1] neg_lo:[0,0,1] neg_hi:[0,0,1]
	s_nop 0
	v_add_f32_e32 v32, v36, v38
.LBB0_669:
	s_or_b64 exec, exec, s[12:13]
	v_cvt_pk_bf16_f32 v32, v32, s0
	ds_write_b16 v179, v32 offset:64
	ds_read_b32 v32, v125 offset:36972
	v_cvt_pk_bf16_f32 v33, v33, s0
	ds_write_b16 v179, v33
	v_mov_b32_e32 v62, v47
	s_waitcnt lgkmcnt(1)
	v_fmamk_f32 v32, v32, 0x3aaaaaab, v233
	v_cmp_gt_f32_e32 vcc, s86, v32
	v_mul_f32_e32 v33, 0x4b800000, v32
	s_nop 0
	v_cndmask_b32_e32 v32, v32, v33, vcc
	v_rsq_f32_e32 v32, v32
	s_nop 0
	v_mul_f32_e32 v33, 0x45800000, v32
	v_cndmask_b32_e32 v32, v32, v33, vcc
	v_mul_f32_e32 v32, 0x3dd53b94, v32
	v_pk_mul_f32 v[32:33], v[62:63], v[32:33] op_sel_hi:[1,0]
	s_and_saveexec_b64 s[12:13], s[4:5]
	s_cbranch_execz .LBB0_671
	s_waitcnt vmcnt(0)
	v_pk_mul_f32 v[38:39], v[32:33], v[218:219] op_sel_hi:[0,1]
	v_pk_mul_f32 v[36:37], v[32:33], v[218:219] op_sel:[1,1] op_sel_hi:[1,0]
	v_pk_fma_f32 v[32:33], v[32:33], v[218:219], v[38:39] op_sel:[1,1,0] op_sel_hi:[1,0,1] neg_lo:[0,0,1] neg_hi:[0,0,1]
	s_nop 0
	v_add_f32_e32 v32, v36, v38
.LBB0_671:
	s_or_b64 exec, exec, s[12:13]
	v_cvt_pk_bf16_f32 v32, v32, s0
	ds_write_b16 v181, v32 offset:64
	ds_read_b32 v32, v125 offset:36992
	v_cvt_pk_bf16_f32 v33, v33, s0
	ds_write_b16 v181, v33
	v_mov_b32_e32 v34, v0
	v_mov_b32_e32 v35, v16
	s_waitcnt lgkmcnt(1)
	v_fmamk_f32 v32, v32, 0x3aaaaaab, v233
	v_cmp_gt_f32_e32 vcc, s86, v32
	v_mul_f32_e32 v33, 0x4b800000, v32
	s_nop 0
	v_cndmask_b32_e32 v32, v32, v33, vcc
	v_rsq_f32_e32 v32, v32
	s_nop 0
	v_mul_f32_e32 v33, 0x45800000, v32
	v_cndmask_b32_e32 v32, v32, v33, vcc
	v_mul_f32_e32 v32, 0x3dd53b94, v32
	v_pk_mul_f32 v[32:33], v[34:35], v[32:33] op_sel_hi:[1,0]
	s_lshl_b32 s39, s36, 7
	s_and_saveexec_b64 s[12:13], s[4:5]
	s_cbranch_execz .Lqrope_b2
	v_add_u32_e32 v220, s39, v150
	v_and_b32_e32 v221, 0xfe4, v220
	v_cmp_gt_i32_e32 vcc, s35, v220
	s_nop 1
	v_cndmask_b32_e32 v220, v126, v221, vcc
	v_lshl_or_b32 v220, v220, 8, v180
	global_load_dwordx2 v[188:189], v220, s[62:63]
	v_add_u32_e32 v220, s39, v151
	v_and_b32_e32 v221, 0xfe5, v220
	v_cmp_gt_i32_e32 vcc, s35, v220
	s_nop 1
	v_cndmask_b32_e32 v220, v129, v221, vcc
	v_lshl_or_b32 v220, v220, 8, v180
	global_load_dwordx2 v[190:191], v220, s[62:63]
	v_add_u32_e32 v220, s39, v152
	v_and_b32_e32 v221, 0xfe6, v220
	v_cmp_gt_i32_e32 vcc, s35, v220
	s_nop 1
	v_cndmask_b32_e32 v220, v131, v221, vcc
	v_lshl_or_b32 v220, v220, 8, v180
	global_load_dwordx2 v[192:193], v220, s[62:63]
	v_add_u32_e32 v220, s39, v153
	v_and_b32_e32 v221, 0xfe7, v220
	v_cmp_gt_i32_e32 vcc, s35, v220
	s_nop 1
	v_cndmask_b32_e32 v220, v133, v221, vcc
	v_lshl_or_b32 v220, v220, 8, v180
	global_load_dwordx2 v[194:195], v220, s[62:63]
	v_add_u32_e32 v220, s39, v154
	v_and_b32_e32 v221, 0xfec, v220
	v_cmp_gt_i32_e32 vcc, s35, v220
	s_nop 1
	v_cndmask_b32_e32 v220, v135, v221, vcc
	v_lshl_or_b32 v220, v220, 8, v180
	global_load_dwordx2 v[196:197], v220, s[62:63]
	v_add_u32_e32 v220, s39, v155
	v_and_b32_e32 v221, 0xfed, v220
	v_cmp_gt_i32_e32 vcc, s35, v220
	s_nop 1
	v_cndmask_b32_e32 v220, v137, v221, vcc
	v_lshl_or_b32 v220, v220, 8, v180
	global_load_dwordx2 v[198:199], v220, s[62:63]
	v_add_u32_e32 v220, s39, v156
	v_and_b32_e32 v221, 0xfee, v220
	v_cmp_gt_i32_e32 vcc, s35, v220
	s_nop 1
	v_cndmask_b32_e32 v220, v139, v221, vcc
	v_lshl_or_b32 v220, v220, 8, v180
	global_load_dwordx2 v[200:201], v220, s[62:63]
	v_add_u32_e32 v220, s39, v157
	v_and_b32_e32 v221, 0xfef, v220
	v_cmp_gt_i32_e32 vcc, s35, v220
	s_nop 1
	v_cndmask_b32_e32 v220, v141, v221, vcc
	v_lshl_or_b32 v220, v220, 8, v180
	global_load_dwordx2 v[202:203], v220, s[62:63]
	v_add_u32_e32 v220, s39, v158
	v_and_b32_e32 v221, 0xff4, v220
	v_cmp_gt_i32_e32 vcc, s35, v220
	s_nop 1
	v_cndmask_b32_e32 v220, v126, v221, vcc
	v_lshl_or_b32 v220, v220, 8, v180
	global_load_dwordx2 v[204:205], v220, s[62:63]
	v_add_u32_e32 v220, s39, v159
	v_and_b32_e32 v221, 0xff5, v220
	v_cmp_gt_i32_e32 vcc, s35, v220
	s_nop 1
	v_cndmask_b32_e32 v220, v129, v221, vcc
	v_lshl_or_b32 v220, v220, 8, v180
	global_load_dwordx2 v[206:207], v220, s[62:63]
	v_add_u32_e32 v220, s39, v160
	v_and_b32_e32 v221, 0xff6, v220
	v_cmp_gt_i32_e32 vcc, s35, v220
	s_nop 1
	v_cndmask_b32_e32 v220, v131, v221, vcc
	v_lshl_or_b32 v220, v220, 8, v180
	global_load_dwordx2 v[208:209], v220, s[62:63]
	v_add_u32_e32 v220, s39, v161
	v_and_b32_e32 v221, 0xff7, v220
	v_cmp_gt_i32_e32 vcc, s35, v220
	s_nop 1
	v_cndmask_b32_e32 v220, v133, v221, vcc
	v_lshl_or_b32 v220, v220, 8, v180
	global_load_dwordx2 v[210:211], v220, s[62:63]
	v_add_u32_e32 v220, s39, v162
	v_and_b32_e32 v221, 0xffc, v220
	v_cmp_gt_i32_e32 vcc, s35, v220
	s_nop 1
	v_cndmask_b32_e32 v220, v135, v221, vcc
	v_lshl_or_b32 v220, v220, 8, v180
	global_load_dwordx2 v[212:213], v220, s[62:63]
	v_add_u32_e32 v220, s39, v163
	v_and_b32_e32 v221, 0xffd, v220
	v_cmp_gt_i32_e32 vcc, s35, v220
	s_nop 1
	v_cndmask_b32_e32 v220, v137, v221, vcc
	v_lshl_or_b32 v220, v220, 8, v180
	global_load_dwordx2 v[214:215], v220, s[62:63]
	v_add_u32_e32 v220, s39, v164
	v_and_b32_e32 v221, 0xffe, v220
	v_cmp_gt_i32_e32 vcc, s35, v220
	s_nop 1
	v_cndmask_b32_e32 v220, v139, v221, vcc
	v_lshl_or_b32 v220, v220, 8, v180
	global_load_dwordx2 v[216:217], v220, s[62:63]
	v_add_u32_e32 v220, s39, v165
	v_and_b32_e32 v221, 0xfff, v220
	v_cmp_gt_i32_e32 vcc, s35, v220
	s_nop 1
	v_cndmask_b32_e32 v220, v141, v221, vcc
	v_lshl_or_b32 v220, v220, 8, v180
	global_load_dwordx2 v[218:219], v220, s[62:63]
; DEV u16 f2bf(float f) { return (u16)(pk2bf(f, 0.f) & 0xffffu); }
; DEV void phase_p2(const Params& p, int l, unsigned char* smem) {
;     ...
;     for (int mi = 0; mi < 2; ++mi)
; #pragma unroll
;       for (int r = 0; r < 16; ++r) {
;         const int row = (w >> 1) * 64 + mi * 32 + (r & 3) + 8 * (r >> 2) + 4 * (lane >> 5);
;         const int m = mt * 128 + row;
;         const float rs = rsqrtf(ss[row] * (1.0f / 768.0f) + EPS) * QSCALE;
;         float v0 = acc[mi][0][r] * rs, v1 = acc[mi][1][r] * rs;
;         if (rope) {
;           const int pos = pos_of(m);
;           const float c = ROPE[(pos * 32 + (lane & 31)) * 2], s = ROPE[(pos * 32 + (lane & 31)) * 2 + 1];
;           const float a = v0 * c - v1 * s, b = v0 * s + v1 * c;
;           v0 = a; v1 = b;
;         }
;         const int col = (w & 1) * 64 + (lane & 31);
;         sC[row * LDC + col] = f2bf(v0);
;         sC[row * LDC + col + 32] = f2bf(v1);
.Lqrope_b2:
	s_or_b64 exec, exec, s[12:13]
	s_and_saveexec_b64 s[12:13], s[4:5]
	s_cbranch_execz .LBB0_673
	s_waitcnt vmcnt(15)
	v_pk_mul_f32 v[38:39], v[32:33], v[188:189] op_sel_hi:[0,1]
	v_pk_mul_f32 v[36:37], v[32:33], v[188:189] op_sel:[1,1] op_sel_hi:[1,0]
	v_pk_fma_f32 v[32:33], v[32:33], v[188:189], v[38:39] op_sel:[1,1,0] op_sel_hi:[1,0,1] neg_lo:[0,0,1] neg_hi:[0,0,1]
	s_nop 0
	v_add_f32_e32 v32, v36, v38
.LBB0_673:
	s_or_b64 exec, exec, s[12:13]
	v_cvt_pk_bf16_f32 v0, v33, s0
	ds_write_b16 v181, v0 offset:1360
	v_cvt_pk_bf16_f32 v0, v32, s0
	ds_write_b16 v181, v0 offset:1424
	ds_read_b32 v0, v125 offset:36996
	s_waitcnt lgkmcnt(0)
	v_fmamk_f32 v0, v0, 0x3aaaaaab, v233
	v_cmp_gt_f32_e32 vcc, s86, v0
	v_mul_f32_e32 v16, 0x4b800000, v0
	s_nop 0
	v_cndmask_b32_e32 v0, v0, v16, vcc
	v_rsq_f32_e32 v0, v0
	s_nop 0
	v_mul_f32_e32 v16, 0x45800000, v0
	v_cndmask_b32_e32 v0, v0, v16, vcc
	v_mul_f32_e32 v0, 0x3dd53b94, v0
	v_mov_b32_e32 v16, v1
	v_pk_mul_f32 v[0:1], v[16:17], v[0:1] op_sel_hi:[1,0]
	s_and_saveexec_b64 s[12:13], s[4:5]
	s_cbranch_execz .LBB0_675
	s_waitcnt vmcnt(14)
	v_pk_mul_f32 v[34:35], v[0:1], v[190:191] op_sel_hi:[0,1]
	v_pk_mul_f32 v[32:33], v[0:1], v[190:191] op_sel:[1,1] op_sel_hi:[1,0]
	v_pk_fma_f32 v[0:1], v[0:1], v[190:191], v[34:35] op_sel:[1,1,0] op_sel_hi:[1,0,1] neg_lo:[0,0,1] neg_hi:[0,0,1]
	s_nop 0
	v_add_f32_e32 v0, v32, v34
.LBB0_675:
	s_or_b64 exec, exec, s[12:13]
	v_cvt_pk_bf16_f32 v0, v0, s0
	ds_write_b16 v181, v0 offset:1696
	ds_read_b32 v0, v125 offset:37000
	v_cvt_pk_bf16_f32 v1, v1, s0
	ds_write_b16 v181, v1 offset:1632
	v_mov_b32_e32 v16, v2
	v_mov_b32_e32 v17, v18
	s_waitcnt lgkmcnt(1)
	v_fmamk_f32 v0, v0, 0x3aaaaaab, v233
	v_cmp_gt_f32_e32 vcc, s86, v0
	v_mul_f32_e32 v1, 0x4b800000, v0
	s_nop 0
	v_cndmask_b32_e32 v0, v0, v1, vcc
	v_rsq_f32_e32 v0, v0
	s_nop 0
	v_mul_f32_e32 v1, 0x45800000, v0
	v_cndmask_b32_e32 v0, v0, v1, vcc
	v_mul_f32_e32 v0, 0x3dd53b94, v0
	v_pk_mul_f32 v[0:1], v[16:17], v[0:1] op_sel_hi:[1,0]
	s_and_saveexec_b64 s[12:13], s[4:5]
	s_cbranch_execz .LBB0_677
	s_waitcnt vmcnt(13)
	v_pk_mul_f32 v[34:35], v[0:1], v[192:193] op_sel_hi:[0,1]
	v_pk_mul_f32 v[32:33], v[0:1], v[192:193] op_sel:[1,1] op_sel_hi:[1,0]
	v_pk_fma_f32 v[0:1], v[0:1], v[192:193], v[34:35] op_sel:[1,1,0] op_sel_hi:[1,0,1] neg_lo:[0,0,1] neg_hi:[0,0,1]
	s_nop 0
	v_add_f32_e32 v0, v32, v34
.LBB0_677:
	s_or_b64 exec, exec, s[12:13]
	v_cvt_pk_bf16_f32 v0, v0, s0
	ds_write_b16 v181, v0 offset:1968
	ds_read_b32 v0, v125 offset:37004
	v_cvt_pk_bf16_f32 v1, v1, s0
	ds_write_b16 v181, v1 offset:1904
	v_mov_b32_e32 v18, v3
	s_waitcnt lgkmcnt(1)
	v_fmamk_f32 v0, v0, 0x3aaaaaab, v233
	v_cmp_gt_f32_e32 vcc, s86, v0
	v_mul_f32_e32 v1, 0x4b800000, v0
	s_nop 0
	v_cndmask_b32_e32 v0, v0, v1, vcc
	v_rsq_f32_e32 v0, v0
	s_nop 0
	v_mul_f32_e32 v1, 0x45800000, v0
	v_cndmask_b32_e32 v0, v0, v1, vcc
	v_mul_f32_e32 v0, 0x3dd53b94, v0
	v_pk_mul_f32 v[0:1], v[18:19], v[0:1] op_sel_hi:[1,0]
	s_and_saveexec_b64 s[12:13], s[4:5]
	s_cbranch_execz .LBB0_679
	s_waitcnt vmcnt(12)
	v_pk_mul_f32 v[18:19], v[0:1], v[194:195] op_sel_hi:[0,1]
	v_pk_mul_f32 v[16:17], v[0:1], v[194:195] op_sel:[1,1] op_sel_hi:[1,0]
	v_pk_fma_f32 v[0:1], v[0:1], v[194:195], v[18:19] op_sel:[1,1,0] op_sel_hi:[1,0,1] neg_lo:[0,0,1] neg_hi:[0,0,1]
	s_nop 0
	v_add_f32_e32 v0, v16, v18
.LBB0_679:
	s_or_b64 exec, exec, s[12:13]
	v_cvt_pk_bf16_f32 v0, v0, s0
	ds_write_b16 v181, v0 offset:2240
	ds_read_b32 v0, v125 offset:37024
	v_cvt_pk_bf16_f32 v1, v1, s0
	ds_write_b16 v181, v1 offset:2176
	v_mov_b32_e32 v2, v4
	v_mov_b32_e32 v3, v20
	s_waitcnt lgkmcnt(1)
	v_fmamk_f32 v0, v0, 0x3aaaaaab, v233
	v_cmp_gt_f32_e32 vcc, s86, v0
	v_mul_f32_e32 v1, 0x4b800000, v0
	s_nop 0
	v_cndmask_b32_e32 v0, v0, v1, vcc
	v_rsq_f32_e32 v0, v0
	s_nop 0
	v_mul_f32_e32 v1, 0x45800000, v0
	v_cndmask_b32_e32 v0, v0, v1, vcc
	v_mul_f32_e32 v0, 0x3dd53b94, v0
	v_pk_mul_f32 v[0:1], v[2:3], v[0:1] op_sel_hi:[1,0]
	s_and_saveexec_b64 s[12:13], s[4:5]
	s_cbranch_execz .LBB0_681
	s_waitcnt vmcnt(11)
	v_pk_mul_f32 v[18:19], v[0:1], v[196:197] op_sel_hi:[0,1]
	v_pk_mul_f32 v[16:17], v[0:1], v[196:197] op_sel:[1,1] op_sel_hi:[1,0]
	v_pk_fma_f32 v[0:1], v[0:1], v[196:197], v[18:19] op_sel:[1,1,0] op_sel_hi:[1,0,1] neg_lo:[0,0,1] neg_hi:[0,0,1]
	s_nop 0
	v_add_f32_e32 v0, v16, v18
.LBB0_681:
	s_or_b64 exec, exec, s[12:13]
	v_cvt_pk_bf16_f32 v0, v0, s0
	ds_write_b16 v181, v0 offset:3600
	ds_read_b32 v0, v125 offset:37028
	v_cvt_pk_bf16_f32 v1, v1, s0
	ds_write_b16 v181, v1 offset:3536
	v_mov_b32_e32 v20, v5
	s_waitcnt lgkmcnt(1)
	v_fmamk_f32 v0, v0, 0x3aaaaaab, v233
	v_cmp_gt_f32_e32 vcc, s86, v0
	v_mul_f32_e32 v1, 0x4b800000, v0
	s_nop 0
	v_cndmask_b32_e32 v0, v0, v1, vcc
	v_rsq_f32_e32 v0, v0
	s_nop 0
	v_mul_f32_e32 v1, 0x45800000, v0
	v_cndmask_b32_e32 v0, v0, v1, vcc
	v_mul_f32_e32 v0, 0x3dd53b94, v0
	v_pk_mul_f32 v[0:1], v[20:21], v[0:1] op_sel_hi:[1,0]
	s_and_saveexec_b64 s[12:13], s[4:5]
	s_cbranch_execz .LBB0_683
	s_waitcnt vmcnt(10)
	v_pk_mul_f32 v[16:17], v[0:1], v[198:199] op_sel_hi:[0,1]
	v_pk_mul_f32 v[4:5], v[0:1], v[198:199] op_sel:[1,1] op_sel_hi:[1,0]
	v_pk_fma_f32 v[0:1], v[0:1], v[198:199], v[16:17] op_sel:[1,1,0] op_sel_hi:[1,0,1] neg_lo:[0,0,1] neg_hi:[0,0,1]
	s_nop 0
	v_add_f32_e32 v0, v4, v16
; DEV u16 f2bf(float f) { return (u16)(pk2bf(f, 0.f) & 0xffffu); }
; DEV void phase_p2(const Params& p, int l, unsigned char* smem) {
;     ...
;     for (int mi = 0; mi < 2; ++mi)
; #pragma unroll
;       for (int r = 0; r < 16; ++r) {
;         const int row = (w >> 1) * 64 + mi * 32 + (r & 3) + 8 * (r >> 2) + 4 * (lane >> 5);
;         const int m = mt * 128 + row;
;         const float rs = rsqrtf(ss[row] * (1.0f / 768.0f) + EPS) * QSCALE;
;         float v0 = acc[mi][0][r] * rs, v1 = acc[mi][1][r] * rs;
;         if (rope) {
;           const int pos = pos_of(m);
;           const float c = ROPE[(pos * 32 + (lane & 31)) * 2], s = ROPE[(pos * 32 + (lane & 31)) * 2 + 1];
;           const float a = v0 * c - v1 * s, b = v0 * s + v1 * c;
;           v0 = a; v1 = b;
;         }
;         const int col = (w & 1) * 64 + (lane & 31);
;         sC[row * LDC + col] = f2bf(v0);
;         sC[row * LDC + col + 32] = f2bf(v1);
.LBB0_683:
	s_or_b64 exec, exec, s[12:13]
	v_cvt_pk_bf16_f32 v0, v0, s0
	ds_write_b16 v181, v0 offset:3872
	ds_read_b32 v0, v125 offset:37032
	v_cvt_pk_bf16_f32 v1, v1, s0
	ds_write_b16 v181, v1 offset:3808
	v_mov_b32_e32 v2, v6
	v_mov_b32_e32 v3, v22
	s_waitcnt lgkmcnt(1)
	v_fmamk_f32 v0, v0, 0x3aaaaaab, v233
	v_cmp_gt_f32_e32 vcc, s86, v0
	v_mul_f32_e32 v1, 0x4b800000, v0
	s_nop 0
	v_cndmask_b32_e32 v0, v0, v1, vcc
	v_rsq_f32_e32 v0, v0
	s_nop 0
	v_mul_f32_e32 v1, 0x45800000, v0
	v_cndmask_b32_e32 v0, v0, v1, vcc
	v_mul_f32_e32 v0, 0x3dd53b94, v0
	v_pk_mul_f32 v[0:1], v[2:3], v[0:1] op_sel_hi:[1,0]
	s_and_saveexec_b64 s[12:13], s[4:5]
	s_cbranch_execz .LBB0_685
	s_waitcnt vmcnt(9)
	v_pk_mul_f32 v[16:17], v[0:1], v[200:201] op_sel_hi:[0,1]
	v_pk_mul_f32 v[4:5], v[0:1], v[200:201] op_sel:[1,1] op_sel_hi:[1,0]
	v_pk_fma_f32 v[0:1], v[0:1], v[200:201], v[16:17] op_sel:[1,1,0] op_sel_hi:[1,0,1] neg_lo:[0,0,1] neg_hi:[0,0,1]
	s_nop 0
	v_add_f32_e32 v0, v4, v16
.LBB0_685:
	s_or_b64 exec, exec, s[12:13]
	v_cvt_pk_bf16_f32 v0, v0, s0
	ds_write_b16 v181, v0 offset:4144
	ds_read_b32 v0, v125 offset:37036
	v_cvt_pk_bf16_f32 v1, v1, s0
	ds_write_b16 v181, v1 offset:4080
	v_mov_b32_e32 v22, v7
	s_waitcnt lgkmcnt(1)
	v_fmamk_f32 v0, v0, 0x3aaaaaab, v233
	v_cmp_gt_f32_e32 vcc, s86, v0
	v_mul_f32_e32 v1, 0x4b800000, v0
	s_nop 0
	v_cndmask_b32_e32 v0, v0, v1, vcc
	v_rsq_f32_e32 v0, v0
	s_nop 0
	v_mul_f32_e32 v1, 0x45800000, v0
	v_cndmask_b32_e32 v0, v0, v1, vcc
	v_mul_f32_e32 v0, 0x3dd53b94, v0
	v_pk_mul_f32 v[0:1], v[22:23], v[0:1] op_sel_hi:[1,0]
	s_and_saveexec_b64 s[12:13], s[4:5]
	s_cbranch_execz .LBB0_687
	s_waitcnt vmcnt(8)
	v_pk_mul_f32 v[6:7], v[0:1], v[202:203] op_sel_hi:[0,1]
	v_pk_mul_f32 v[4:5], v[0:1], v[202:203] op_sel:[1,1] op_sel_hi:[1,0]
	v_pk_fma_f32 v[0:1], v[0:1], v[202:203], v[6:7] op_sel:[1,1,0] op_sel_hi:[1,0,1] neg_lo:[0,0,1] neg_hi:[0,0,1]
	s_nop 0
	v_add_f32_e32 v0, v4, v6
.LBB0_687:
	s_or_b64 exec, exec, s[12:13]
	v_cvt_pk_bf16_f32 v0, v0, s0
	ds_write_b16 v181, v0 offset:4416
	ds_read_b32 v0, v125 offset:37056
	v_cvt_pk_bf16_f32 v1, v1, s0
	ds_write_b16 v181, v1 offset:4352
	v_mov_b32_e32 v2, v8
	v_mov_b32_e32 v3, v24
	s_waitcnt lgkmcnt(1)
	v_fmamk_f32 v0, v0, 0x3aaaaaab, v233
	v_cmp_gt_f32_e32 vcc, s86, v0
	v_mul_f32_e32 v1, 0x4b800000, v0
	s_nop 0
	v_cndmask_b32_e32 v0, v0, v1, vcc
	v_rsq_f32_e32 v0, v0
	s_nop 0
	v_mul_f32_e32 v1, 0x45800000, v0
	v_cndmask_b32_e32 v0, v0, v1, vcc
	v_mul_f32_e32 v0, 0x3dd53b94, v0
	v_pk_mul_f32 v[0:1], v[2:3], v[0:1] op_sel_hi:[1,0]
	s_and_saveexec_b64 s[12:13], s[4:5]
	s_cbranch_execz .LBB0_689
	s_waitcnt vmcnt(7)
	v_pk_mul_f32 v[6:7], v[0:1], v[204:205] op_sel_hi:[0,1]
	v_pk_mul_f32 v[4:5], v[0:1], v[204:205] op_sel:[1,1] op_sel_hi:[1,0]
	v_pk_fma_f32 v[0:1], v[0:1], v[204:205], v[6:7] op_sel:[1,1,0] op_sel_hi:[1,0,1] neg_lo:[0,0,1] neg_hi:[0,0,1]
	s_nop 0
	v_add_f32_e32 v0, v4, v6
.LBB0_689:
	s_or_b64 exec, exec, s[12:13]
	v_cvt_pk_bf16_f32 v0, v0, s0
	ds_write_b16 v181, v0 offset:5776
	ds_read_b32 v0, v125 offset:37060
	v_cvt_pk_bf16_f32 v1, v1, s0
	ds_write_b16 v181, v1 offset:5712
	v_mov_b32_e32 v24, v9
	s_waitcnt lgkmcnt(1)
	v_fmamk_f32 v0, v0, 0x3aaaaaab, v233
	v_cmp_gt_f32_e32 vcc, s86, v0
	v_mul_f32_e32 v1, 0x4b800000, v0
	s_nop 0
	v_cndmask_b32_e32 v0, v0, v1, vcc
	v_rsq_f32_e32 v0, v0
	s_nop 0
	v_mul_f32_e32 v1, 0x45800000, v0
	v_cndmask_b32_e32 v0, v0, v1, vcc
	v_mul_f32_e32 v0, 0x3dd53b94, v0
	v_pk_mul_f32 v[0:1], v[24:25], v[0:1] op_sel_hi:[1,0]
	s_and_saveexec_b64 s[12:13], s[4:5]
	s_cbranch_execz .LBB0_691
	s_waitcnt vmcnt(6)
	v_pk_mul_f32 v[6:7], v[0:1], v[206:207] op_sel_hi:[0,1]
	v_pk_mul_f32 v[4:5], v[0:1], v[206:207] op_sel:[1,1] op_sel_hi:[1,0]
	v_pk_fma_f32 v[0:1], v[0:1], v[206:207], v[6:7] op_sel:[1,1,0] op_sel_hi:[1,0,1] neg_lo:[0,0,1] neg_hi:[0,0,1]
	s_nop 0
	v_add_f32_e32 v0, v4, v6
.LBB0_691:
	s_or_b64 exec, exec, s[12:13]
	v_cvt_pk_bf16_f32 v0, v0, s0
	ds_write_b16 v181, v0 offset:6048
	ds_read_b32 v0, v125 offset:37064
	v_cvt_pk_bf16_f32 v1, v1, s0
	ds_write_b16 v181, v1 offset:5984
	v_mov_b32_e32 v2, v10
	v_mov_b32_e32 v3, v26
	s_waitcnt lgkmcnt(1)
	v_fmamk_f32 v0, v0, 0x3aaaaaab, v233
	v_cmp_gt_f32_e32 vcc, s86, v0
	v_mul_f32_e32 v1, 0x4b800000, v0
	s_nop 0
	v_cndmask_b32_e32 v0, v0, v1, vcc
	v_rsq_f32_e32 v0, v0
	s_nop 0
	v_mul_f32_e32 v1, 0x45800000, v0
	v_cndmask_b32_e32 v0, v0, v1, vcc
	v_mul_f32_e32 v0, 0x3dd53b94, v0
	v_pk_mul_f32 v[0:1], v[2:3], v[0:1] op_sel_hi:[1,0]
	s_and_saveexec_b64 s[12:13], s[4:5]
	s_cbranch_execz .LBB0_693
	s_waitcnt vmcnt(5)
	v_pk_mul_f32 v[6:7], v[0:1], v[208:209] op_sel_hi:[0,1]
	v_pk_mul_f32 v[4:5], v[0:1], v[208:209] op_sel:[1,1] op_sel_hi:[1,0]
	v_pk_fma_f32 v[0:1], v[0:1], v[208:209], v[6:7] op_sel:[1,1,0] op_sel_hi:[1,0,1] neg_lo:[0,0,1] neg_hi:[0,0,1]
	s_nop 0
	v_add_f32_e32 v0, v4, v6
; DEV u16 f2bf(float f) { return (u16)(pk2bf(f, 0.f) & 0xffffu); }
; DEV void phase_p2(const Params& p, int l, unsigned char* smem) {
;     ...
;     for (int mi = 0; mi < 2; ++mi)
; #pragma unroll
;       for (int r = 0; r < 16; ++r) {
;         const int row = (w >> 1) * 64 + mi * 32 + (r & 3) + 8 * (r >> 2) + 4 * (lane >> 5);
;         const int m = mt * 128 + row;
;         const float rs = rsqrtf(ss[row] * (1.0f / 768.0f) + EPS) * QSCALE;
;         float v0 = acc[mi][0][r] * rs, v1 = acc[mi][1][r] * rs;
;         if (rope) {
;           const int pos = pos_of(m);
;           const float c = ROPE[(pos * 32 + (lane & 31)) * 2], s = ROPE[(pos * 32 + (lane & 31)) * 2 + 1];
;           const float a = v0 * c - v1 * s, b = v0 * s + v1 * c;
;           v0 = a; v1 = b;
;         }
;         const int col = (w & 1) * 64 + (lane & 31);
;         sC[row * LDC + col] = f2bf(v0);
;         sC[row * LDC + col + 32] = f2bf(v1);
.LBB0_693:
	s_or_b64 exec, exec, s[12:13]
	v_cvt_pk_bf16_f32 v0, v0, s0
	ds_write_b16 v181, v0 offset:6320
	ds_read_b32 v0, v125 offset:37068
	v_cvt_pk_bf16_f32 v1, v1, s0
	ds_write_b16 v181, v1 offset:6256
	v_mov_b32_e32 v26, v11
	s_waitcnt lgkmcnt(1)
	v_fmamk_f32 v0, v0, 0x3aaaaaab, v233
	v_cmp_gt_f32_e32 vcc, s86, v0
	v_mul_f32_e32 v1, 0x4b800000, v0
	s_nop 0
	v_cndmask_b32_e32 v0, v0, v1, vcc
	v_rsq_f32_e32 v0, v0
	s_nop 0
	v_mul_f32_e32 v1, 0x45800000, v0
	v_cndmask_b32_e32 v0, v0, v1, vcc
	v_mul_f32_e32 v0, 0x3dd53b94, v0
	v_pk_mul_f32 v[0:1], v[26:27], v[0:1] op_sel_hi:[1,0]
	s_and_saveexec_b64 s[12:13], s[4:5]
	s_cbranch_execz .LBB0_695
	s_waitcnt vmcnt(4)
	v_pk_mul_f32 v[6:7], v[0:1], v[210:211] op_sel_hi:[0,1]
	v_pk_mul_f32 v[4:5], v[0:1], v[210:211] op_sel:[1,1] op_sel_hi:[1,0]
	v_pk_fma_f32 v[0:1], v[0:1], v[210:211], v[6:7] op_sel:[1,1,0] op_sel_hi:[1,0,1] neg_lo:[0,0,1] neg_hi:[0,0,1]
	s_nop 0
	v_add_f32_e32 v0, v4, v6
.LBB0_695:
	s_or_b64 exec, exec, s[12:13]
	v_cvt_pk_bf16_f32 v0, v0, s0
	ds_write_b16 v181, v0 offset:6592
	ds_read_b32 v0, v125 offset:37088
	v_cvt_pk_bf16_f32 v1, v1, s0
	ds_write_b16 v181, v1 offset:6528
	v_mov_b32_e32 v2, v12
	v_mov_b32_e32 v3, v28
	s_waitcnt lgkmcnt(1)
	v_fmamk_f32 v0, v0, 0x3aaaaaab, v233
	v_cmp_gt_f32_e32 vcc, s86, v0
	v_mul_f32_e32 v1, 0x4b800000, v0
	s_nop 0
	v_cndmask_b32_e32 v0, v0, v1, vcc
	v_rsq_f32_e32 v0, v0
	s_nop 0
	v_mul_f32_e32 v1, 0x45800000, v0
	v_cndmask_b32_e32 v0, v0, v1, vcc
	v_mul_f32_e32 v0, 0x3dd53b94, v0
	v_pk_mul_f32 v[0:1], v[2:3], v[0:1] op_sel_hi:[1,0]
	s_and_saveexec_b64 s[12:13], s[4:5]
	s_cbranch_execz .LBB0_697
	s_waitcnt vmcnt(3)
	v_pk_mul_f32 v[6:7], v[0:1], v[212:213] op_sel_hi:[0,1]
	v_pk_mul_f32 v[4:5], v[0:1], v[212:213] op_sel:[1,1] op_sel_hi:[1,0]
	v_pk_fma_f32 v[0:1], v[0:1], v[212:213], v[6:7] op_sel:[1,1,0] op_sel_hi:[1,0,1] neg_lo:[0,0,1] neg_hi:[0,0,1]
	s_nop 0
	v_add_f32_e32 v0, v4, v6
.LBB0_697:
	s_or_b64 exec, exec, s[12:13]
	v_cvt_pk_bf16_f32 v0, v0, s0
	ds_write_b16 v181, v0 offset:7952
	ds_read_b32 v0, v125 offset:37092
	v_cvt_pk_bf16_f32 v1, v1, s0
	ds_write_b16 v181, v1 offset:7888
	v_mov_b32_e32 v28, v13
	s_waitcnt lgkmcnt(1)
	v_fmamk_f32 v0, v0, 0x3aaaaaab, v233
	v_cmp_gt_f32_e32 vcc, s86, v0
	v_mul_f32_e32 v1, 0x4b800000, v0
	s_nop 0
	v_cndmask_b32_e32 v0, v0, v1, vcc
	v_rsq_f32_e32 v0, v0
	s_nop 0
	v_mul_f32_e32 v1, 0x45800000, v0
	v_cndmask_b32_e32 v0, v0, v1, vcc
	v_mul_f32_e32 v0, 0x3dd53b94, v0
	v_pk_mul_f32 v[0:1], v[28:29], v[0:1] op_sel_hi:[1,0]
	s_and_saveexec_b64 s[12:13], s[4:5]
	s_cbranch_execz .LBB0_699
	s_waitcnt vmcnt(2)
	v_pk_mul_f32 v[6:7], v[0:1], v[214:215] op_sel_hi:[0,1]
	v_pk_mul_f32 v[4:5], v[0:1], v[214:215] op_sel:[1,1] op_sel_hi:[1,0]
	v_pk_fma_f32 v[0:1], v[0:1], v[214:215], v[6:7] op_sel:[1,1,0] op_sel_hi:[1,0,1] neg_lo:[0,0,1] neg_hi:[0,0,1]
	s_nop 0
	v_add_f32_e32 v0, v4, v6
.LBB0_699:
	s_or_b64 exec, exec, s[12:13]
	v_cvt_pk_bf16_f32 v0, v0, s0
	ds_write_b16 v181, v0 offset:8224
	ds_read_b32 v0, v125 offset:37096
	v_cvt_pk_bf16_f32 v1, v1, s0
	ds_write_b16 v181, v1 offset:8160
	v_mov_b32_e32 v2, v14
	v_mov_b32_e32 v3, v30
	s_waitcnt lgkmcnt(1)
	v_fmamk_f32 v0, v0, 0x3aaaaaab, v233
	v_cmp_gt_f32_e32 vcc, s86, v0
	v_mul_f32_e32 v1, 0x4b800000, v0
	s_nop 0
	v_cndmask_b32_e32 v0, v0, v1, vcc
	v_rsq_f32_e32 v0, v0
	s_nop 0
	v_mul_f32_e32 v1, 0x45800000, v0
	v_cndmask_b32_e32 v0, v0, v1, vcc
	v_mul_f32_e32 v0, 0x3dd53b94, v0
	v_pk_mul_f32 v[0:1], v[2:3], v[0:1] op_sel_hi:[1,0]
	s_and_saveexec_b64 s[12:13], s[4:5]
	s_cbranch_execz .LBB0_701
	s_waitcnt vmcnt(1)
	v_pk_mul_f32 v[6:7], v[0:1], v[216:217] op_sel_hi:[0,1]
	v_pk_mul_f32 v[4:5], v[0:1], v[216:217] op_sel:[1,1] op_sel_hi:[1,0]
	v_pk_fma_f32 v[0:1], v[0:1], v[216:217], v[6:7] op_sel:[1,1,0] op_sel_hi:[1,0,1] neg_lo:[0,0,1] neg_hi:[0,0,1]
	s_nop 0
	v_add_f32_e32 v0, v4, v6
.LBB0_701:
	s_or_b64 exec, exec, s[12:13]
	v_cvt_pk_bf16_f32 v0, v0, s0
	ds_write_b16 v181, v0 offset:8496
	ds_read_b32 v0, v125 offset:37100
	v_cvt_pk_bf16_f32 v1, v1, s0
	ds_write_b16 v181, v1 offset:8432
	v_mov_b32_e32 v30, v15
	s_waitcnt lgkmcnt(1)
	v_fmamk_f32 v0, v0, 0x3aaaaaab, v233
	v_cmp_gt_f32_e32 vcc, s86, v0
	v_mul_f32_e32 v1, 0x4b800000, v0
	s_nop 0
	v_cndmask_b32_e32 v0, v0, v1, vcc
	v_rsq_f32_e32 v0, v0
	s_nop 0
	v_mul_f32_e32 v1, 0x45800000, v0
	v_cndmask_b32_e32 v0, v0, v1, vcc
	v_mul_f32_e32 v0, 0x3dd53b94, v0
	v_pk_mul_f32 v[0:1], v[30:31], v[0:1] op_sel_hi:[1,0]
	s_and_saveexec_b64 s[12:13], s[4:5]
	s_cbranch_execz .LBB0_703
	s_waitcnt vmcnt(0)
	v_pk_mul_f32 v[6:7], v[0:1], v[218:219] op_sel_hi:[0,1]
	v_pk_mul_f32 v[4:5], v[0:1], v[218:219] op_sel:[1,1] op_sel_hi:[1,0]
	v_pk_fma_f32 v[0:1], v[0:1], v[218:219], v[6:7] op_sel:[1,1,0] op_sel_hi:[1,0,1] neg_lo:[0,0,1] neg_hi:[0,0,1]
	s_nop 0
	v_add_f32_e32 v0, v4, v6
